# up-GEMM epilogue: row-scale loads prefetched at unit head into 2 VGPRs and broadcast with ds_bpermute; 8 serialized vmcnt(0) round trips removed
# speedup vs baseline: 1.0057x; 1.0057x over previous
;   __device__ __forceinline__ bool next(int i,AttnUnit&u)const{ if(i>=2)return false; const int s=vcu&15; u.bh=vcu>>4; u.qb=(i==0)?31-s:s; return true; }
; #define RS ((float*)(WSP() + WS_RS))
;     __host__ __device__ bool next(int i, Unit& u) const {
;         const long L = (long)i * G + c; if (L >= nwg) return false;
;         int wgid = (int)L; { const int q = nwg / NXCD, r = nwg % NXCD, xcd = wgid % NXCD, off = wgid / NXCD; wgid = (xcd < r ? xcd * (q + 1) : r * (q + 1) + (xcd - r) * q) + off; }
;         const int nig = WGM * nN, gid = wgid / nig, fm = gid * WGM, gsz = (nM - fm) < WGM ? (nM - fm) : WGM;
;         u.pm = fm + ((wgid % nig) % gsz); u.pn = (wgid % nig) / gsz; return true;
;     __device__ __forceinline__ void operator()(const f32x4 (&acc)[2][2][4][2], const Unit& u, int wr, int wc, int fr, int fq) const {
;     ...
;             for (int m = 0; m < 4; ++m) { const size_t off = (size_t)(row0 + ai * HALF + m * 16) * ldc + col0; const float rs = (MODE != 0) ? RS[row0 + ai * HALF + m * 16] : 1.f;
.LBB0_672:
	v_and_b32_e32 v140, 63, v200
	v_and_b32_e32 v141, 0xffffffc0, v144
	v_or_b32_e32 v140, v140, v141
	v_lshl_add_u32 v140, s22, 8, v140
	v_ashrrev_i32_e32 v141, 31, v140
	v_lshl_add_u64 v[140:141], v[140:141], 2, s[10:11]
	global_load_dword v252, v[140:141], off
	global_load_dword v253, v[140:141], off offset:512
	s_add_i32 s74, s74, 1
	s_mul_i32 s4, s74, s73
	s_mul_hi_u32 s5, s74, s2
	s_add_i32 s5, s5, s4
	s_mul_i32 s4, s74, s2
	s_add_u32 s18, s4, s30
	s_addc_u32 s19, s5, s31
	v_mov_b64_e32 v[2:3], 0x800
	v_cmp_gt_i64_e32 vcc, s[18:19], v[192:193]
	v_cmp_lt_i64_e64 s[4:5], s[18:19], v[2:3]
	s_cbranch_vccnz .LBB0_678
	s_ashr_i32 s14, s18, 31
	s_lshr_b32 s14, s14, 29
	s_add_i32 s16, s18, s14
	s_and_b32 s14, s16, -8
	s_sub_i32 s17, s18, s14
	s_cmp_gt_i32 s17, -1
	s_mov_b64 s[14:15], -1
	s_cbranch_scc0 .LBB0_675
	s_lshl_b32 s18, s17, 8
	s_mov_b64 s[14:15], 0

; __device__ __forceinline__ unsigned cvt_pk_bf16(float lo, float hi) { unsigned r; asm volatile("v_cvt_pk_bf16_f32 %0, %1, %2" : "=v"(r) : "v"(lo), "v"(hi)); return r; }
; __device__ __forceinline__ float bf_lo(unsigned w) { return __uint_as_float(w << 16); }
; __device__ __forceinline__ float bf_hi(unsigned w) { return __uint_as_float(w & 0xffff0000u); }
; __device__ __forceinline__ float sigmoid_f(float x) { return __builtin_amdgcn_rcpf(1.0f + __builtin_amdgcn_exp2f(-1.4426950408889634f * x)); }
; #define RS ((float*)(WSP() + WS_RS))
;     __device__ __forceinline__ void operator()(const f32x4 (&acc)[2][2][4][2], const Unit& u, int wr, int wc, int fr, int fq) const {
;     ...
;             for (int m = 0; m < 4; ++m) { const size_t off = (size_t)(row0 + ai * HALF + m * 16) * ldc + col0; const float rs = (MODE != 0) ? RS[row0 + ai * HALF + m * 16] : 1.f;
; #pragma unroll
;                 for (int bj = 0; bj < 2; ++bj) { f32x4 v0 = acc[ai][bj][m][0], v1 = acc[ai][bj][m][1];
;                     if (MODE != 0) { v0 = v0 * rs; v1 = v1 * rs; }
;                     if (MODE == 1) {
; #pragma unroll
;                         for (int e = 0; e < 4; ++e) { const float a = fmaxf(v0[e], 0.f), b = fmaxf(v1[e], 0.f); v0[e] = a * a; v1[e] = b * b; } }
;                     if (MODE == 2) { v0 = v0 * sc; v1 = v1 * sc; }
;                     if (MODE == 3) { const u32x4 pw = *(const u32x4*)(P + off + bj * HALF);
;                         v0[0] = bf_lo(pw.x) * sigmoid_f(v0[0]); v0[1] = bf_hi(pw.x) * sigmoid_f(v0[1]); v0[2] = bf_lo(pw.y) * sigmoid_f(v0[2]); v0[3] = bf_hi(pw.y) * sigmoid_f(v0[3]);
;                         v1[0] = bf_lo(pw.z) * sigmoid_f(v1[0]); v1[1] = bf_hi(pw.z) * sigmoid_f(v1[1]); v1[2] = bf_lo(pw.w) * sigmoid_f(v1[2]); v1[3] = bf_hi(pw.w) * sigmoid_f(v1[3]); }
;                     u32x4 w; w.x = cvt_pk_bf16(v0[0], v0[1]); w.y = cvt_pk_bf16(v0[2], v0[3]); w.z = cvt_pk_bf16(v1[0], v1[1]); w.w = cvt_pk_bf16(v1[2], v1[3]);
;                     *(u32x4*)(O + off + bj * HALF) = w; } }
.LBB0_682:
	v_and_b32_e32 v152, 15, v200
	v_lshlrev_b32_e32 v152, 2, v152
	v_add_u32_e32 v153, 64, v152
	v_add_u32_e32 v154, 0x80, v152
	v_add_u32_e32 v155, 0xc0, v152
	ds_bpermute_b32 v160, v152, v252
	ds_bpermute_b32 v161, v153, v252
	ds_bpermute_b32 v162, v154, v252
	ds_bpermute_b32 v163, v155, v252
	ds_bpermute_b32 v164, v152, v253
	ds_bpermute_b32 v165, v153, v253
	ds_bpermute_b32 v166, v154, v253
	ds_bpermute_b32 v167, v155, v253
	s_waitcnt lgkmcnt(0)
	v_lshl_add_u32 v142, s22, 8, v144
	v_ashrrev_i32_e32 v143, 31, v142
	v_lshl_add_u64 v[140:141], v[142:143], 2, s[10:11]
	s_nop 1
	v_mov_b32_e32 v150, v160
	v_lshl_or_b32 v148, s23, 8, v146
	v_ashrrev_i32_e32 v149, 31, v148
	s_mov_b32 s15, 0x100000
	s_mov_b64 s[22:23], 0x100000
	v_pk_mul_f32 v[128:129], v[128:129], v[150:151] op_sel_hi:[1,0]
	v_pk_mul_f32 v[126:127], v[126:127], v[150:151] op_sel_hi:[1,0]
	v_pk_mul_f32 v[122:123], v[122:123], v[150:151] op_sel_hi:[1,0]
	v_pk_mul_f32 v[124:125], v[124:125], v[150:151] op_sel_hi:[1,0]
	v_max_f32_e32 v126, 0, v126
	v_max_f32_e32 v122, 0, v122
	v_max_f32_e32 v127, 0, v127
	v_max_f32_e32 v123, 0, v123
	v_max_f32_e32 v128, 0, v128
	v_mul_f32_e32 v126, v126, v126
	v_mul_f32_e32 v122, v122, v122
	v_mul_f32_e32 v127, v127, v127
	v_mul_f32_e32 v123, v123, v123
	v_max_f32_e32 v124, 0, v124
	v_mul_f32_e32 v128, v128, v128
	v_max_f32_e32 v129, 0, v129
	v_max_f32_e32 v125, 0, v125
	v_mul_f32_e32 v124, v124, v124
	v_mul_f32_e32 v129, v129, v129
	v_mul_f32_e32 v125, v125, v125
	v_cvt_pk_bf16_f32 v126, v126, v127
	v_cvt_pk_bf16_f32 v127, v128, v129
	v_cvt_pk_bf16_f32 v128, v122, v123
	v_lshlrev_b64 v[122:123], 13, v[142:143]
	v_cvt_pk_bf16_f32 v129, v124, v125
	v_lshl_add_u64 v[122:123], s[8:9], 0, v[122:123]
	v_lshlrev_b64 v[124:125], 1, v[148:149]
	v_pk_mul_f32 v[114:115], v[114:115], v[150:151] op_sel_hi:[1,0]
	v_lshl_add_u64 v[122:123], v[122:123], 0, v[124:125]
	v_pk_mul_f32 v[118:119], v[118:119], v[150:151] op_sel_hi:[1,0]
	v_pk_mul_f32 v[116:117], v[116:117], v[150:151] op_sel_hi:[1,0]
	v_max_f32_e32 v114, 0, v114
	global_store_dwordx4 v[122:123], v[126:129], off
	v_pk_mul_f32 v[120:121], v[120:121], v[150:151] op_sel_hi:[1,0]
	v_max_f32_e32 v115, 0, v115
	v_mul_f32_e32 v126, v114, v114
	v_max_f32_e32 v114, 0, v119
	v_max_f32_e32 v116, 0, v116
	v_max_f32_e32 v118, 0, v118
	v_mul_f32_e32 v114, v114, v114
	v_mul_f32_e32 v119, v115, v115
	v_max_f32_e32 v115, 0, v120
	v_mul_f32_e32 v120, v116, v116
	v_max_f32_e32 v116, 0, v121
	v_max_f32_e32 v117, 0, v117
	v_mul_f32_e32 v118, v118, v118
	v_mul_f32_e32 v115, v115, v115
	v_mul_f32_e32 v116, v116, v116
	v_mul_f32_e32 v117, v117, v117
	v_cvt_pk_bf16_f32 v114, v118, v114
	v_cvt_pk_bf16_f32 v115, v115, v116
	v_cvt_pk_bf16_f32 v116, v126, v119
	v_cvt_pk_bf16_f32 v117, v120, v117
	global_store_dwordx4 v[122:123], v[114:117], off offset:256
	s_nop 1
	v_or_b32_e32 v114, 16, v142
	v_ashrrev_i32_e32 v115, 31, v114
	v_lshl_add_u64 v[116:117], v[114:115], 2, s[10:11]
	s_nop 1
	v_mov_b32_e32 v116, v161
	v_pk_mul_f32 v[108:109], v[108:109], v[116:117] op_sel_hi:[1,0]
	v_pk_mul_f32 v[106:107], v[106:107], v[116:117] op_sel_hi:[1,0]
	v_pk_mul_f32 v[112:113], v[112:113], v[116:117] op_sel_hi:[1,0]
	v_pk_mul_f32 v[110:111], v[110:111], v[116:117] op_sel_hi:[1,0]
	v_max_f32_e32 v106, 0, v106
	v_max_f32_e32 v107, 0, v107
	v_max_f32_e32 v108, 0, v108
	v_max_f32_e32 v110, 0, v110
	v_mul_f32_e32 v117, v106, v106
	v_max_f32_e32 v106, 0, v111
	v_mul_f32_e32 v111, v107, v107
	v_max_f32_e32 v107, 0, v112
	v_mul_f32_e32 v112, v108, v108
	v_max_f32_e32 v108, 0, v113
	v_mul_f32_e32 v110, v110, v110
	v_mul_f32_e32 v106, v106, v106
	v_mul_f32_e32 v107, v107, v107
	v_mul_f32_e32 v108, v108, v108
	v_cvt_pk_bf16_f32 v106, v110, v106
	v_cvt_pk_bf16_f32 v107, v107, v108
	v_cvt_pk_bf16_f32 v108, v117, v111
	v_lshlrev_b64 v[110:111], 13, v[114:115]
	v_max_f32_e32 v109, 0, v109
	v_lshl_add_u64 v[110:111], s[8:9], 0, v[110:111]
	v_pk_mul_f32 v[98:99], v[98:99], v[116:117] op_sel_hi:[1,0]
	v_mul_f32_e32 v109, v109, v109
	v_lshl_add_u64 v[110:111], v[110:111], 0, v[124:125]
	v_pk_mul_f32 v[102:103], v[102:103], v[116:117] op_sel_hi:[1,0]
	v_pk_mul_f32 v[100:101], v[100:101], v[116:117] op_sel_hi:[1,0]
	v_max_f32_e32 v98, 0, v98
	v_cvt_pk_bf16_f32 v109, v112, v109
	global_store_dwordx4 v[110:111], v[106:109], off
	v_pk_mul_f32 v[104:105], v[104:105], v[116:117] op_sel_hi:[1,0]
	v_max_f32_e32 v99, 0, v99
	v_mul_f32_e32 v106, v98, v98
	v_max_f32_e32 v98, 0, v103
	v_max_f32_e32 v100, 0, v100
	v_max_f32_e32 v102, 0, v102
	v_mul_f32_e32 v98, v98, v98
	v_mul_f32_e32 v103, v99, v99
	v_max_f32_e32 v99, 0, v104
	v_mul_f32_e32 v104, v100, v100
	v_max_f32_e32 v100, 0, v105
	v_max_f32_e32 v101, 0, v101
	v_mul_f32_e32 v102, v102, v102
	v_mul_f32_e32 v99, v99, v99
	v_mul_f32_e32 v100, v100, v100
	v_mul_f32_e32 v101, v101, v101
	v_cvt_pk_bf16_f32 v98, v102, v98
	v_cvt_pk_bf16_f32 v99, v99, v100
	v_cvt_pk_bf16_f32 v100, v106, v103
	v_cvt_pk_bf16_f32 v101, v104, v101
	global_store_dwordx4 v[110:111], v[98:101], off offset:256
	s_nop 1
	v_or_b32_e32 v98, 32, v142
	v_ashrrev_i32_e32 v99, 31, v98
	v_lshl_add_u64 v[100:101], v[98:99], 2, s[10:11]
	s_nop 1
	v_mov_b32_e32 v100, v162
	v_pk_mul_f32 v[92:93], v[92:93], v[100:101] op_sel_hi:[1,0]
	v_pk_mul_f32 v[90:91], v[90:91], v[100:101] op_sel_hi:[1,0]
	v_pk_mul_f32 v[96:97], v[96:97], v[100:101] op_sel_hi:[1,0]
	v_pk_mul_f32 v[94:95], v[94:95], v[100:101] op_sel_hi:[1,0]
	v_max_f32_e32 v90, 0, v90
	v_max_f32_e32 v91, 0, v91
	v_max_f32_e32 v92, 0, v92
	v_max_f32_e32 v94, 0, v94
	v_mul_f32_e32 v101, v90, v90
	v_max_f32_e32 v90, 0, v95
	v_mul_f32_e32 v95, v91, v91
	v_max_f32_e32 v91, 0, v96
	v_mul_f32_e32 v96, v92, v92
; __device__ __forceinline__ unsigned cvt_pk_bf16(float lo, float hi) { unsigned r; asm volatile("v_cvt_pk_bf16_f32 %0, %1, %2" : "=v"(r) : "v"(lo), "v"(hi)); return r; }
; __device__ __forceinline__ float bf_lo(unsigned w) { return __uint_as_float(w << 16); }
; __device__ __forceinline__ float bf_hi(unsigned w) { return __uint_as_float(w & 0xffff0000u); }
; __device__ __forceinline__ float sigmoid_f(float x) { return __builtin_amdgcn_rcpf(1.0f + __builtin_amdgcn_exp2f(-1.4426950408889634f * x)); }
; #define RS ((float*)(WSP() + WS_RS))
;     __device__ __forceinline__ void operator()(const f32x4 (&acc)[2][2][4][2], const Unit& u, int wr, int wc, int fr, int fq) const {
;     ...
;             for (int m = 0; m < 4; ++m) { const size_t off = (size_t)(row0 + ai * HALF + m * 16) * ldc + col0; const float rs = (MODE != 0) ? RS[row0 + ai * HALF + m * 16] : 1.f;
; #pragma unroll
;                 for (int bj = 0; bj < 2; ++bj) { f32x4 v0 = acc[ai][bj][m][0], v1 = acc[ai][bj][m][1];
;                     if (MODE != 0) { v0 = v0 * rs; v1 = v1 * rs; }
;                     if (MODE == 1) {
; #pragma unroll
;                         for (int e = 0; e < 4; ++e) { const float a = fmaxf(v0[e], 0.f), b = fmaxf(v1[e], 0.f); v0[e] = a * a; v1[e] = b * b; } }
;                     if (MODE == 2) { v0 = v0 * sc; v1 = v1 * sc; }
;                     if (MODE == 3) { const u32x4 pw = *(const u32x4*)(P + off + bj * HALF);
;                         v0[0] = bf_lo(pw.x) * sigmoid_f(v0[0]); v0[1] = bf_hi(pw.x) * sigmoid_f(v0[1]); v0[2] = bf_lo(pw.y) * sigmoid_f(v0[2]); v0[3] = bf_hi(pw.y) * sigmoid_f(v0[3]);
;                         v1[0] = bf_lo(pw.z) * sigmoid_f(v1[0]); v1[1] = bf_hi(pw.z) * sigmoid_f(v1[1]); v1[2] = bf_lo(pw.w) * sigmoid_f(v1[2]); v1[3] = bf_hi(pw.w) * sigmoid_f(v1[3]); }
;                     u32x4 w; w.x = cvt_pk_bf16(v0[0], v0[1]); w.y = cvt_pk_bf16(v0[2], v0[3]); w.z = cvt_pk_bf16(v1[0], v1[1]); w.w = cvt_pk_bf16(v1[2], v1[3]);
;                     *(u32x4*)(O + off + bj * HALF) = w; } }
	v_max_f32_e32 v92, 0, v97
	v_mul_f32_e32 v94, v94, v94
	v_mul_f32_e32 v90, v90, v90
	v_mul_f32_e32 v91, v91, v91
	v_mul_f32_e32 v92, v92, v92
	v_cvt_pk_bf16_f32 v90, v94, v90
	v_cvt_pk_bf16_f32 v91, v91, v92
	v_cvt_pk_bf16_f32 v92, v101, v95
	v_lshlrev_b64 v[94:95], 13, v[98:99]
	v_max_f32_e32 v93, 0, v93
	v_lshl_add_u64 v[94:95], s[8:9], 0, v[94:95]
	v_pk_mul_f32 v[82:83], v[82:83], v[100:101] op_sel_hi:[1,0]
	v_mul_f32_e32 v93, v93, v93
	v_lshl_add_u64 v[94:95], v[94:95], 0, v[124:125]
	v_pk_mul_f32 v[86:87], v[86:87], v[100:101] op_sel_hi:[1,0]
	v_pk_mul_f32 v[84:85], v[84:85], v[100:101] op_sel_hi:[1,0]
	v_max_f32_e32 v82, 0, v82
	v_cvt_pk_bf16_f32 v93, v96, v93
	global_store_dwordx4 v[94:95], v[90:93], off
	v_pk_mul_f32 v[88:89], v[88:89], v[100:101] op_sel_hi:[1,0]
	v_max_f32_e32 v83, 0, v83
	v_mul_f32_e32 v90, v82, v82
	v_max_f32_e32 v82, 0, v87
	v_max_f32_e32 v84, 0, v84
	v_max_f32_e32 v86, 0, v86
	v_mul_f32_e32 v82, v82, v82
	v_mul_f32_e32 v87, v83, v83
	v_max_f32_e32 v83, 0, v88
	v_mul_f32_e32 v88, v84, v84
	v_max_f32_e32 v84, 0, v89
	v_max_f32_e32 v85, 0, v85
	v_mul_f32_e32 v86, v86, v86
	v_mul_f32_e32 v83, v83, v83
	v_mul_f32_e32 v84, v84, v84
	v_mul_f32_e32 v85, v85, v85
	v_cvt_pk_bf16_f32 v82, v86, v82
	v_cvt_pk_bf16_f32 v83, v83, v84
	v_cvt_pk_bf16_f32 v84, v90, v87
	v_cvt_pk_bf16_f32 v85, v88, v85
	global_store_dwordx4 v[94:95], v[82:85], off offset:256
	s_nop 1
	v_or_b32_e32 v82, 48, v142
	v_ashrrev_i32_e32 v83, 31, v82
	v_lshl_add_u64 v[84:85], v[82:83], 2, s[10:11]
	s_nop 1
	v_mov_b32_e32 v84, v163
	v_pk_mul_f32 v[76:77], v[76:77], v[84:85] op_sel_hi:[1,0]
	v_pk_mul_f32 v[74:75], v[74:75], v[84:85] op_sel_hi:[1,0]
	v_pk_mul_f32 v[80:81], v[80:81], v[84:85] op_sel_hi:[1,0]
	v_pk_mul_f32 v[78:79], v[78:79], v[84:85] op_sel_hi:[1,0]
	v_max_f32_e32 v74, 0, v74
	v_max_f32_e32 v75, 0, v75
	v_max_f32_e32 v76, 0, v76
	v_max_f32_e32 v78, 0, v78
	v_mul_f32_e32 v85, v74, v74
	v_max_f32_e32 v74, 0, v79
	v_mul_f32_e32 v79, v75, v75
	v_max_f32_e32 v75, 0, v80
	v_mul_f32_e32 v80, v76, v76
	v_max_f32_e32 v76, 0, v81
	v_mul_f32_e32 v78, v78, v78
	v_mul_f32_e32 v74, v74, v74
	v_mul_f32_e32 v75, v75, v75
	v_mul_f32_e32 v76, v76, v76
	v_cvt_pk_bf16_f32 v74, v78, v74
	v_cvt_pk_bf16_f32 v75, v75, v76
	v_cvt_pk_bf16_f32 v76, v85, v79
	v_lshlrev_b64 v[78:79], 13, v[82:83]
	v_max_f32_e32 v77, 0, v77
	v_lshl_add_u64 v[78:79], s[8:9], 0, v[78:79]
	v_pk_mul_f32 v[68:69], v[68:69], v[84:85] op_sel_hi:[1,0]
	v_pk_mul_f32 v[66:67], v[66:67], v[84:85] op_sel_hi:[1,0]
	v_mul_f32_e32 v77, v77, v77
	v_lshl_add_u64 v[78:79], v[78:79], 0, v[124:125]
	v_pk_mul_f32 v[72:73], v[72:73], v[84:85] op_sel_hi:[1,0]
	v_pk_mul_f32 v[70:71], v[70:71], v[84:85] op_sel_hi:[1,0]
	v_max_f32_e32 v66, 0, v66
	v_max_f32_e32 v67, 0, v67
	v_max_f32_e32 v68, 0, v68
	v_cvt_pk_bf16_f32 v77, v80, v77
	global_store_dwordx4 v[78:79], v[74:77], off
	v_max_f32_e32 v69, 0, v69
	v_max_f32_e32 v70, 0, v70
	v_mul_f32_e32 v74, v66, v66
	v_max_f32_e32 v66, 0, v71
	v_mul_f32_e32 v71, v67, v67
	v_max_f32_e32 v67, 0, v72
	v_mul_f32_e32 v72, v68, v68
	v_max_f32_e32 v68, 0, v73
	v_mul_f32_e32 v66, v66, v66
	v_mul_f32_e32 v67, v67, v67
	v_mul_f32_e32 v68, v68, v68
	v_mul_f32_e32 v69, v69, v69
	v_mul_f32_e32 v70, v70, v70
	v_cvt_pk_bf16_f32 v66, v70, v66
	v_cvt_pk_bf16_f32 v67, v67, v68
	v_cvt_pk_bf16_f32 v68, v74, v71
	v_cvt_pk_bf16_f32 v69, v72, v69
	global_store_dwordx4 v[78:79], v[66:69], off offset:256
	s_nop 1
	v_mov_b32_e32 v66, v164
	v_pk_mul_f32 v[60:61], v[60:61], v[66:67] op_sel_hi:[1,0]
	v_pk_mul_f32 v[58:59], v[58:59], v[66:67] op_sel_hi:[1,0]
	v_pk_mul_f32 v[64:65], v[64:65], v[66:67] op_sel_hi:[1,0]
	v_pk_mul_f32 v[62:63], v[62:63], v[66:67] op_sel_hi:[1,0]
	v_max_f32_e32 v58, 0, v58
	v_max_f32_e32 v59, 0, v59
	v_max_f32_e32 v60, 0, v60
	v_mul_f32_e32 v67, v58, v58
	v_max_f32_e32 v58, 0, v63
	v_mul_f32_e32 v63, v59, v59
	v_max_f32_e32 v59, 0, v64
	v_mul_f32_e32 v64, v60, v60
	v_max_f32_e32 v60, 0, v65
	v_max_f32_e32 v61, 0, v61
	v_max_f32_e32 v62, 0, v62
	v_mul_f32_e32 v58, v58, v58
	v_mul_f32_e32 v59, v59, v59
	v_mul_f32_e32 v60, v60, v60
	v_mul_f32_e32 v61, v61, v61
	v_mul_f32_e32 v62, v62, v62
	v_cvt_pk_bf16_f32 v58, v62, v58
	v_cvt_pk_bf16_f32 v59, v59, v60
	v_cvt_pk_bf16_f32 v60, v67, v63
	v_cvt_pk_bf16_f32 v61, v64, v61
	v_add_co_u32_e32 v64, vcc, s15, v122
	v_pk_mul_f32 v[52:53], v[52:53], v[66:67] op_sel_hi:[1,0]
	v_pk_mul_f32 v[50:51], v[50:51], v[66:67] op_sel_hi:[1,0]
	v_addc_co_u32_e32 v65, vcc, 0, v123, vcc
	v_pk_mul_f32 v[56:57], v[56:57], v[66:67] op_sel_hi:[1,0]
	v_pk_mul_f32 v[54:55], v[54:55], v[66:67] op_sel_hi:[1,0]
	v_max_f32_e32 v50, 0, v50
	v_max_f32_e32 v51, 0, v51
	v_max_f32_e32 v52, 0, v52
	global_store_dwordx4 v[64:65], v[58:61], off
	v_max_f32_e32 v53, 0, v53
	v_lshl_add_u64 v[62:63], v[122:123], 0, s[22:23]
	v_mul_f32_e32 v58, v50, v50
	v_max_f32_e32 v50, 0, v55
	v_mul_f32_e32 v55, v51, v51
	v_max_f32_e32 v51, 0, v56
	v_mul_f32_e32 v56, v52, v52
	v_max_f32_e32 v52, 0, v57
	v_max_f32_e32 v54, 0, v54
	v_mul_f32_e32 v50, v50, v50
	v_mul_f32_e32 v51, v51, v51
	v_mul_f32_e32 v52, v52, v52
	v_mul_f32_e32 v53, v53, v53
	v_mul_f32_e32 v54, v54, v54
	v_cvt_pk_bf16_f32 v50, v54, v50
	v_cvt_pk_bf16_f32 v51, v51, v52
	v_cvt_pk_bf16_f32 v52, v58, v55
	v_cvt_pk_bf16_f32 v53, v56, v53
	global_store_dwordx4 v[62:63], v[50:53], off offset:256
	s_nop 1
	v_mov_b32_e32 v50, v165
	s_mov_b32 s15, 0x120000
	s_mov_b64 s[22:23], 0x120000
	v_pk_mul_f32 v[48:49], v[48:49], v[50:51] op_sel_hi:[1,0]
	v_pk_mul_f32 v[44:45], v[44:45], v[50:51] op_sel_hi:[1,0]
	v_pk_mul_f32 v[46:47], v[46:47], v[50:51] op_sel_hi:[1,0]
	v_max_f32_e32 v48, 0, v48
	v_max_f32_e32 v44, 0, v44
; __device__ __forceinline__ unsigned cvt_pk_bf16(float lo, float hi) { unsigned r; asm volatile("v_cvt_pk_bf16_f32 %0, %1, %2" : "=v"(r) : "v"(lo), "v"(hi)); return r; }
;     __device__ __forceinline__ void operator()(const f32x4 (&acc)[2][2][4][2], const Unit& u, int wr, int wc, int fr, int fq) const {
;     ...
;             for (int m = 0; m < 4; ++m) { const size_t off = (size_t)(row0 + ai * HALF + m * 16) * ldc + col0; const float rs = (MODE != 0) ? RS[row0 + ai * HALF + m * 16] : 1.f;
; #pragma unroll
;                 for (int bj = 0; bj < 2; ++bj) { f32x4 v0 = acc[ai][bj][m][0], v1 = acc[ai][bj][m][1];
;                     if (MODE != 0) { v0 = v0 * rs; v1 = v1 * rs; }
;                     if (MODE == 1) {
; #pragma unroll
;                         for (int e = 0; e < 4; ++e) { const float a = fmaxf(v0[e], 0.f), b = fmaxf(v1[e], 0.f); v0[e] = a * a; v1[e] = b * b; } }
;                     if (MODE == 2) { v0 = v0 * sc; v1 = v1 * sc; }
;                     if (MODE == 3) { const u32x4 pw = *(const u32x4*)(P + off + bj * HALF);
;                         v0[0] = bf_lo(pw.x) * sigmoid_f(v0[0]); v0[1] = bf_hi(pw.x) * sigmoid_f(v0[1]); v0[2] = bf_lo(pw.y) * sigmoid_f(v0[2]); v0[3] = bf_hi(pw.y) * sigmoid_f(v0[3]);
;                         v1[0] = bf_lo(pw.z) * sigmoid_f(v1[0]); v1[1] = bf_hi(pw.z) * sigmoid_f(v1[1]); v1[2] = bf_lo(pw.w) * sigmoid_f(v1[2]); v1[3] = bf_hi(pw.w) * sigmoid_f(v1[3]); }
;                     u32x4 w; w.x = cvt_pk_bf16(v0[0], v0[1]); w.y = cvt_pk_bf16(v0[2], v0[3]); w.z = cvt_pk_bf16(v1[0], v1[1]); w.w = cvt_pk_bf16(v1[2], v1[3]);
;                     *(u32x4*)(O + off + bj * HALF) = w; } }
; template <class Epi, class Sched, bool ALIGN_EPI = false, bool SP2 = false>
; __device__ __forceinline__ void gemm_phase(PG8_LAS unsigned char* lds, const Gemm g, const Sched& S, const Epi& E, int tid_in) {
;     ...
;         if (!has_next) break;
; #pragma unroll
;         for (int a = 0; a < 2; ++a)
; #pragma unroll
;             for (int b = 0; b < 2; ++b)
; #pragma unroll
;                 for (int m = 0; m < 4; ++m)
; #pragma unroll
;                     for (int n = 0; n < 2; ++n) acc[a][b][m][n] = (f32x4){0.f, 0.f, 0.f, 0.f};
;         cur = nxt; cA = nA; cB = nB; ++ui;
;         if constexpr (ALIGN_EPI) { if (wr == 1) PG8_BAR; }
;     }
;     PG8_WAIT_V(0);
;     if constexpr (!ALIGN_EPI) { if (wr == 0) PG8_BAR; }
;     PG8_BAR;
	v_pk_mul_f32 v[42:43], v[42:43], v[50:51] op_sel_hi:[1,0]
	v_max_f32_e32 v46, 0, v46
	v_max_f32_e32 v47, 0, v47
	v_mul_f32_e32 v48, v48, v48
	v_mul_f32_e32 v51, v44, v44
	v_max_f32_e32 v44, 0, v49
	v_max_f32_e32 v45, 0, v45
	v_mul_f32_e32 v46, v46, v46
	v_mul_f32_e32 v47, v47, v47
	v_mul_f32_e32 v49, v44, v44
	v_mul_f32_e32 v52, v45, v45
	v_cvt_pk_bf16_f32 v44, v46, v47
	v_cvt_pk_bf16_f32 v45, v48, v49
	v_add_co_u32_e32 v48, vcc, s15, v122
	v_pk_mul_f32 v[36:37], v[36:37], v[50:51] op_sel_hi:[1,0]
	v_pk_mul_f32 v[34:35], v[34:35], v[50:51] op_sel_hi:[1,0]
	v_max_f32_e32 v42, 0, v42
	v_max_f32_e32 v43, 0, v43
	v_addc_co_u32_e32 v49, vcc, 0, v123, vcc
	v_pk_mul_f32 v[40:41], v[40:41], v[50:51] op_sel_hi:[1,0]
	v_pk_mul_f32 v[38:39], v[38:39], v[50:51] op_sel_hi:[1,0]
	v_max_f32_e32 v34, 0, v34
	v_max_f32_e32 v35, 0, v35
	v_max_f32_e32 v36, 0, v36
	v_mul_f32_e32 v42, v42, v42
	v_mul_f32_e32 v43, v43, v43
	v_cvt_pk_bf16_f32 v46, v42, v43
	v_cvt_pk_bf16_f32 v47, v51, v52
	global_store_dwordx4 v[48:49], v[44:47], off
	v_max_f32_e32 v37, 0, v37
	v_lshl_add_u64 v[42:43], v[122:123], 0, s[22:23]
	v_mul_f32_e32 v44, v34, v34
	v_max_f32_e32 v34, 0, v39
	v_mul_f32_e32 v39, v35, v35
	v_max_f32_e32 v35, 0, v40
	v_mul_f32_e32 v40, v36, v36
	v_max_f32_e32 v36, 0, v41
	v_max_f32_e32 v38, 0, v38
	v_mul_f32_e32 v34, v34, v34
	v_mul_f32_e32 v35, v35, v35
	v_mul_f32_e32 v36, v36, v36
	v_mul_f32_e32 v37, v37, v37
	v_mul_f32_e32 v38, v38, v38
	v_cvt_pk_bf16_f32 v34, v38, v34
	v_cvt_pk_bf16_f32 v35, v35, v36
	v_cvt_pk_bf16_f32 v36, v44, v39
	v_cvt_pk_bf16_f32 v37, v40, v37
	global_store_dwordx4 v[42:43], v[34:37], off offset:256
	s_nop 1
	v_mov_b32_e32 v34, v166
	s_mov_b32 s15, 0x140000
	s_mov_b64 s[22:23], 0x140000
	v_pk_mul_f32 v[32:33], v[32:33], v[34:35] op_sel_hi:[1,0]
	v_pk_mul_f32 v[28:29], v[28:29], v[34:35] op_sel_hi:[1,0]
	v_pk_mul_f32 v[30:31], v[30:31], v[34:35] op_sel_hi:[1,0]
	v_max_f32_e32 v32, 0, v32
	v_max_f32_e32 v28, 0, v28
	v_pk_mul_f32 v[26:27], v[26:27], v[34:35] op_sel_hi:[1,0]
	v_max_f32_e32 v30, 0, v30
	v_max_f32_e32 v31, 0, v31
	v_mul_f32_e32 v32, v32, v32
	v_mul_f32_e32 v35, v28, v28
	v_max_f32_e32 v28, 0, v33
	v_max_f32_e32 v29, 0, v29
	v_mul_f32_e32 v30, v30, v30
	v_mul_f32_e32 v31, v31, v31
	v_mul_f32_e32 v33, v28, v28
	v_mul_f32_e32 v36, v29, v29
	v_cvt_pk_bf16_f32 v28, v30, v31
	v_cvt_pk_bf16_f32 v29, v32, v33
	v_add_co_u32_e32 v32, vcc, s15, v122
	v_pk_mul_f32 v[20:21], v[20:21], v[34:35] op_sel_hi:[1,0]
	v_pk_mul_f32 v[18:19], v[18:19], v[34:35] op_sel_hi:[1,0]
	v_max_f32_e32 v26, 0, v26
	v_max_f32_e32 v27, 0, v27
	v_addc_co_u32_e32 v33, vcc, 0, v123, vcc
	v_pk_mul_f32 v[24:25], v[24:25], v[34:35] op_sel_hi:[1,0]
	v_pk_mul_f32 v[22:23], v[22:23], v[34:35] op_sel_hi:[1,0]
	v_max_f32_e32 v18, 0, v18
	v_max_f32_e32 v19, 0, v19
	v_max_f32_e32 v20, 0, v20
	v_mul_f32_e32 v26, v26, v26
	v_mul_f32_e32 v27, v27, v27
	v_cvt_pk_bf16_f32 v30, v26, v27
	v_cvt_pk_bf16_f32 v31, v35, v36
	global_store_dwordx4 v[32:33], v[28:31], off
	v_max_f32_e32 v21, 0, v21
	v_lshl_add_u64 v[26:27], v[122:123], 0, s[22:23]
	v_mul_f32_e32 v28, v18, v18
	v_max_f32_e32 v18, 0, v23
	v_mul_f32_e32 v23, v19, v19
	v_max_f32_e32 v19, 0, v24
	v_mul_f32_e32 v24, v20, v20
	v_max_f32_e32 v20, 0, v25
	v_max_f32_e32 v22, 0, v22
	v_mul_f32_e32 v18, v18, v18
	v_mul_f32_e32 v19, v19, v19
	v_mul_f32_e32 v20, v20, v20
	v_mul_f32_e32 v21, v21, v21
	v_mul_f32_e32 v22, v22, v22
	v_cvt_pk_bf16_f32 v18, v22, v18
	v_cvt_pk_bf16_f32 v19, v19, v20
	v_cvt_pk_bf16_f32 v20, v28, v23
	v_cvt_pk_bf16_f32 v21, v24, v21
	global_store_dwordx4 v[26:27], v[18:21], off offset:256
	s_nop 1
	v_mov_b32_e32 v18, v167
	s_mov_b32 s15, 0x160000
	s_mov_b64 s[22:23], 0x160000
	v_pk_mul_f32 v[12:13], v[12:13], v[18:19] op_sel_hi:[1,0]
	v_pk_mul_f32 v[10:11], v[10:11], v[18:19] op_sel_hi:[1,0]
	v_pk_mul_f32 v[16:17], v[16:17], v[18:19] op_sel_hi:[1,0]
	v_pk_mul_f32 v[14:15], v[14:15], v[18:19] op_sel_hi:[1,0]
	v_max_f32_e32 v10, 0, v10
	v_max_f32_e32 v11, 0, v11
	v_max_f32_e32 v12, 0, v12
	v_mul_f32_e32 v19, v10, v10
	v_max_f32_e32 v10, 0, v15
	v_mul_f32_e32 v15, v11, v11
	v_max_f32_e32 v11, 0, v16
	v_mul_f32_e32 v16, v12, v12
	v_max_f32_e32 v12, 0, v17
	v_max_f32_e32 v13, 0, v13
	v_max_f32_e32 v14, 0, v14
	v_mul_f32_e32 v10, v10, v10
	v_mul_f32_e32 v11, v11, v11
	v_mul_f32_e32 v12, v12, v12
	v_mul_f32_e32 v13, v13, v13
	v_mul_f32_e32 v14, v14, v14
	v_cvt_pk_bf16_f32 v10, v14, v10
	v_cvt_pk_bf16_f32 v11, v11, v12
	v_cvt_pk_bf16_f32 v12, v19, v15
	v_cvt_pk_bf16_f32 v13, v16, v13
	v_add_co_u32_e32 v16, vcc, s15, v122
	v_pk_mul_f32 v[4:5], v[4:5], v[18:19] op_sel_hi:[1,0]
	v_pk_mul_f32 v[2:3], v[2:3], v[18:19] op_sel_hi:[1,0]
	v_addc_co_u32_e32 v17, vcc, 0, v123, vcc
	v_pk_mul_f32 v[8:9], v[8:9], v[18:19] op_sel_hi:[1,0]
	v_pk_mul_f32 v[6:7], v[6:7], v[18:19] op_sel_hi:[1,0]
	v_max_f32_e32 v2, 0, v2
	v_max_f32_e32 v3, 0, v3
	v_max_f32_e32 v4, 0, v4
	global_store_dwordx4 v[16:17], v[10:13], off
	v_max_f32_e32 v5, 0, v5
	v_lshl_add_u64 v[14:15], v[122:123], 0, s[22:23]
	v_mul_f32_e32 v10, v2, v2
	v_max_f32_e32 v2, 0, v7
	v_mul_f32_e32 v7, v3, v3
	v_max_f32_e32 v3, 0, v8
	v_mul_f32_e32 v8, v4, v4
	v_max_f32_e32 v4, 0, v9
	v_max_f32_e32 v6, 0, v6
	v_mul_f32_e32 v2, v2, v2
	v_mul_f32_e32 v3, v3, v3
	v_mul_f32_e32 v4, v4, v4
	v_mul_f32_e32 v5, v5, v5
	s_mov_b64 s[22:23], -1
	s_andn2_b64 vcc, exec, s[4:5]
	v_mul_f32_e32 v6, v6, v6
	v_cvt_pk_bf16_f32 v2, v6, v2
	v_cvt_pk_bf16_f32 v3, v3, v4
	v_cvt_pk_bf16_f32 v4, v10, v7
	v_cvt_pk_bf16_f32 v5, v8, v5
	global_store_dwordx4 v[14:15], v[2:5], off offset:256
	s_cbranch_vccnz .LBB0_671
	s_andn2_b64 vcc, exec, s[6:7]
	s_cbranch_vccnz .LBB0_670
	s_barrier
	s_branch .LBB0_670
